# G6 ring version with the late-wave DMA group issued one K-step earlier (after the first K-step)
# baseline (speedup 1.0000x reference)
.LBB0_228:
	s_or_b64 exec, exec, s[6:7]
	s_add_i32 s6, s13, 0
	v_add_u32_e32 v131, s6, v182
	v_add_u32_e32 v133, v131, v184
	v_add_u32_e32 v130, v246, v183
	ds_read_b128 v[190:193], v133
	ds_read_b128 v[194:197], v133 offset:4096
	ds_read_b128 v[198:201], v133 offset:8192
	v_add_u32_e32 v133, v130, v184
	ds_read_b128 v[206:209], v133 offset:32768
	ds_read_b128 v[210:213], v133 offset:36864
	s_setprio 1
	s_waitcnt lgkmcnt(0)
	v_mfma_f32_32x32x16_bf16 v[112:127], v[190:193], v[206:209], v[112:127]
	v_mfma_f32_32x32x16_bf16 v[96:111], v[190:193], v[210:213], v[96:111]
	v_mfma_f32_32x32x16_bf16 v[80:95], v[194:197], v[206:209], v[80:95]
	v_mfma_f32_32x32x16_bf16 v[64:79], v[194:197], v[210:213], v[64:79]
	v_mfma_f32_32x32x16_bf16 v[48:63], v[198:201], v[206:209], v[48:63]
	v_mfma_f32_32x32x16_bf16 v[32:47], v[198:201], v[210:213], v[32:47]
	s_setprio 0
	s_and_saveexec_b64 s[6:7], s[0:1]
	s_cbranch_execz .LBB0_230
	s_xor_b32 s14, s13, 0x22000
	v_add_u32_e32 v133, s14, v180
	v_lshl_add_u64 v[190:191], v[150:151], 0, s[4:5]
	v_readfirstlane_b32 s15, v133
	s_nop 0
	s_mov_b32 m0, s15
	s_nop 0
	global_load_lds_dwordx4 v[190:191], off
	v_add_u32_e32 v133, s14, v179
	v_lshl_add_u64 v[190:191], v[152:153], 0, s[4:5]
	v_readfirstlane_b32 s15, v133
	s_nop 0
	s_mov_b32 m0, s15
	s_nop 0
	global_load_lds_dwordx4 v[190:191], off
	v_add_u32_e32 v133, s14, v178
	v_lshl_add_u64 v[190:191], v[154:155], 0, s[4:5]
	v_readfirstlane_b32 s15, v133
	s_nop 0
	s_mov_b32 m0, s15
	s_nop 0
	global_load_lds_dwordx4 v[190:191], off
	v_add_u32_e32 v249, 0x8000, v248
	v_add_u32_e32 v133, v249, v180
	v_lshl_add_u64 v[190:191], v[158:159], 0, s[4:5]
	v_readfirstlane_b32 s15, v133
	s_nop 0
	s_mov_b32 m0, s15
	s_nop 0
	global_load_lds_dwordx4 v[190:191], off
	v_add_u32_e32 v133, v249, v179
	v_lshl_add_u64 v[190:191], v[160:161], 0, s[4:5]
	v_readfirstlane_b32 s15, v133
	s_nop 0
	s_mov_b32 m0, s15
	s_nop 0
	global_load_lds_dwordx4 v[190:191], off
	v_add_u32_e32 v133, v249, v178
	v_lshl_add_u64 v[190:191], v[162:163], 0, s[4:5]
	v_readfirstlane_b32 s15, v133
	s_nop 0
	s_mov_b32 m0, s15
	s_nop 0
	global_load_lds_dwordx4 v[190:191], off
	v_add_u32_e32 v133, v249, v177
	v_lshl_add_u64 v[190:191], v[164:165], 0, s[4:5]
	v_readfirstlane_b32 s15, v133
	s_nop 0
	s_mov_b32 m0, s15
	s_nop 0
	global_load_lds_dwordx4 v[190:191], off
.LBB0_230:
	s_or_b64 exec, exec, s[6:7]
	v_add_u32_e32 v133, v131, v181
	ds_read_b128 v[190:193], v133
	ds_read_b128 v[194:197], v133 offset:4096
	ds_read_b128 v[198:201], v133 offset:8192
	v_add_u32_e32 v133, v130, v181
	ds_read_b128 v[206:209], v133 offset:32768
	ds_read_b128 v[210:213], v133 offset:36864
	s_setprio 1
	s_waitcnt lgkmcnt(0)
	v_mfma_f32_32x32x16_bf16 v[112:127], v[190:193], v[206:209], v[112:127]
	v_mfma_f32_32x32x16_bf16 v[96:111], v[190:193], v[210:213], v[96:111]
	v_mfma_f32_32x32x16_bf16 v[80:95], v[194:197], v[206:209], v[80:95]
	v_mfma_f32_32x32x16_bf16 v[64:79], v[194:197], v[210:213], v[64:79]
	v_mfma_f32_32x32x16_bf16 v[48:63], v[198:201], v[206:209], v[48:63]
	v_mfma_f32_32x32x16_bf16 v[32:47], v[198:201], v[210:213], v[32:47]
	s_setprio 0
	v_add_u32_e32 v133, v131, v172
	ds_read_b128 v[190:193], v133
	ds_read_b128 v[194:197], v133 offset:4096
	ds_read_b128 v[198:201], v133 offset:8192
	v_add_u32_e32 v133, v130, v172
	ds_read_b128 v[206:209], v133 offset:32768
	ds_read_b128 v[210:213], v133 offset:36864
	s_setprio 1
	s_waitcnt lgkmcnt(0)
	v_mfma_f32_32x32x16_bf16 v[112:127], v[190:193], v[206:209], v[112:127]
	v_mfma_f32_32x32x16_bf16 v[96:111], v[190:193], v[210:213], v[96:111]
	v_mfma_f32_32x32x16_bf16 v[80:95], v[194:197], v[206:209], v[80:95]
	v_mfma_f32_32x32x16_bf16 v[64:79], v[194:197], v[210:213], v[64:79]
	v_mfma_f32_32x32x16_bf16 v[48:63], v[198:201], v[206:209], v[48:63]
	v_mfma_f32_32x32x16_bf16 v[32:47], v[198:201], v[210:213], v[32:47]
	s_setprio 0
	v_add_u32_e32 v131, v131, v171
	ds_read_b128 v[190:193], v131
	ds_read_b128 v[194:197], v131 offset:4096
	ds_read_b128 v[198:201], v131 offset:8192
	v_add_u32_e32 v130, v130, v171
	ds_read_b128 v[206:209], v130 offset:32768
	ds_read_b128 v[210:213], v130 offset:36864
	s_setprio 1
	s_waitcnt lgkmcnt(0)
	v_mfma_f32_32x32x16_bf16 v[112:127], v[190:193], v[206:209], v[112:127]
	v_mfma_f32_32x32x16_bf16 v[96:111], v[190:193], v[210:213], v[96:111]
	v_mfma_f32_32x32x16_bf16 v[80:95], v[194:197], v[206:209], v[80:95]
	v_mfma_f32_32x32x16_bf16 v[64:79], v[194:197], v[210:213], v[64:79]
	v_mfma_f32_32x32x16_bf16 v[48:63], v[198:201], v[206:209], v[48:63]
	v_mfma_f32_32x32x16_bf16 v[32:47], v[198:201], v[210:213], v[32:47]
	s_setprio 0
	s_xor_b32 s6, s9, 1
	v_mov_b32_e32 v249, v246
	v_mov_b32_e32 v246, v247
	v_mov_b32_e32 v247, v248
	v_mov_b32_e32 v248, v249
	s_waitcnt vmcnt(4)
	s_add_u32 s4, s4, 0x80
	s_addc_u32 s5, s5, 0
	s_cmpk_lg_i32 s4, 0x1f80
	s_waitcnt vmcnt(4)
	s_barrier
	s_cbranch_scc1 .LBB0_226
	v_add_u32_e32 v147, s8, v128
	v_cmp_lt_i32_e64 s[0:1], 31, v147
	s_xor_b64 s[4:5], vcc, -1
	s_nor_b64 s[4:5], s[4:5], s[0:1]
	v_cndmask_b32_e64 v128, v147, v128, s[0:1]
	v_ashrrev_i32_e32 v130, 31, v128
	v_lshrrev_b32_e32 v130, 30, v130
	v_add_u32_e32 v130, v128, v130
	v_lshrrev_b32_e32 v131, 2, v130
	v_and_b32_e32 v130, 0xfffffc, v130
	v_sub_u32_e32 v130, v128, v130
	v_lshlrev_b32_e32 v128, 4, v132
	v_and_b32_e32 v128, 0x70, v128
	v_add_lshl_u32 v146, v131, v166, 8
	v_lshl_add_u64 v[136:137], s[38:39], 0, v[128:129]
	v_lshl_add_u64 v[134:135], s[40:41], 0, v[128:129]
	v_lshlrev_b32_e32 v148, 8, v130
	s_and_saveexec_b64 s[14:15], s[4:5]
	s_xor_b64 s[4:5], exec, s[14:15]
	s_cbranch_execz .LBB0_233
	s_lshl_b32 s7, s6, 16
	s_xor_b32 s13, s7, 0x10000
	v_add_u32_e32 v130, v146, v188
	s_add_i32 s13, s13, 0
	v_ashrrev_i32_e32 v131, 31, v130
	v_add_u32_e32 v132, v187, v146
	v_add_u32_e32 v128, s13, v180
	v_lshlrev_b64 v[130:131], 13, v[130:131]
	v_ashrrev_i32_e32 v133, 31, v132
	v_readfirstlane_b32 s14, v128
	v_add_u32_e32 v142, s13, v179
	v_lshl_add_u64 v[130:131], v[136:137], 0, v[130:131]
	v_lshlrev_b64 v[132:133], 13, v[132:133]
	s_mov_b32 m0, s14
	v_readfirstlane_b32 s14, v142
	v_lshl_add_u64 v[132:133], v[136:137], 0, v[132:133]
	v_add_u32_e32 v138, v186, v146
	global_load_lds_dwordx4 v[130:131], off
	s_mov_b32 m0, s14
	v_ashrrev_i32_e32 v139, 31, v138
	v_add_u32_e32 v140, v185, v146
	global_load_lds_dwordx4 v[132:133], off
	v_add_u32_e32 v132, s13, v178
	v_lshlrev_b64 v[138:139], 13, v[138:139]
	v_ashrrev_i32_e32 v141, 31, v140
	v_readfirstlane_b32 s14, v132
	v_add_u32_e32 v133, s13, v177
	v_add_u32_e32 v130, v148, v188
	v_lshl_add_u64 v[138:139], v[136:137], 0, v[138:139]
	v_lshlrev_b64 v[140:141], 13, v[140:141]
	s_mov_b32 m0, s14
	v_readfirstlane_b32 s13, v133
	v_ashrrev_i32_e32 v131, 31, v130
	v_add_u32_e32 v128, 0x8000, v128
	v_lshl_add_u64 v[140:141], v[136:137], 0, v[140:141]
	global_load_lds_dwordx4 v[138:139], off
	s_mov_b32 m0, s13
	v_lshlrev_b64 v[130:131], 13, v[130:131]
	v_readfirstlane_b32 s13, v128
	global_load_lds_dwordx4 v[140:141], off
	v_lshl_add_u64 v[130:131], v[134:135], 0, v[130:131]
	s_mov_b32 m0, s13
	v_add_u32_e32 v128, 0x8000, v142
	global_load_lds_dwordx4 v[130:131], off
	v_add_u32_e32 v130, v187, v148
	v_ashrrev_i32_e32 v131, 31, v130
	v_lshlrev_b64 v[130:131], 13, v[130:131]
	v_readfirstlane_b32 s13, v128
	v_lshl_add_u64 v[130:131], v[134:135], 0, v[130:131]
	s_mov_b32 m0, s13
	v_add_u32_e32 v128, 0x8000, v132
	global_load_lds_dwordx4 v[130:131], off
	v_add_u32_e32 v130, v186, v148
	v_ashrrev_i32_e32 v131, 31, v130
	v_lshlrev_b64 v[130:131], 13, v[130:131]
	v_readfirstlane_b32 s13, v128
	v_lshl_add_u64 v[130:131], v[134:135], 0, v[130:131]
	s_mov_b32 m0, s13
	v_add_u32_e32 v128, 0x8000, v133
	global_load_lds_dwordx4 v[130:131], off
	v_add_u32_e32 v130, v185, v148
	v_ashrrev_i32_e32 v131, 31, v130
	v_lshlrev_b64 v[130:131], 13, v[130:131]
	v_readfirstlane_b32 s13, v128
	v_lshl_add_u64 v[130:131], v[134:135], 0, v[130:131]
	s_mov_b32 m0, s13
	s_nop 0
	global_load_lds_dwordx4 v[130:131], off
